# grid barrier: all waiters poll the cross-XCD arrival counter directly (no separate release word hop)
# speedup vs baseline: 1.0044x; 1.0044x over previous
.LBB0_406:
	s_or_b64 exec, exec, s[4:5]
	v_cvt_f32_u32_e32 v5, v3
	s_waitcnt vmcnt(0)
	v_readfirstlane_b32 s2, v4
	v_sub_u32_e32 v4, 0, v3
	v_rcp_iflag_f32_e32 v5, v5
	v_add_u32_e32 v6, s2, v0
	v_mul_f32_e32 v5, 0x4f7ffffe, v5
	v_cvt_u32_f32_e32 v5, v5
	v_mul_lo_u32 v0, v4, v5
	v_mul_hi_u32 v0, v5, v0
	v_add_u32_e32 v0, v5, v0
	v_mul_hi_u32 v0, v6, v0
	v_mul_lo_u32 v4, v0, v3
	v_sub_u32_e32 v4, v6, v4
	v_add_u32_e32 v5, 1, v0
	v_cmp_ge_u32_e32 vcc, v4, v3
	s_nop 1
	v_cndmask_b32_e32 v0, v0, v5, vcc
	v_sub_u32_e32 v5, v4, v3
	v_cndmask_b32_e32 v4, v4, v5, vcc
	v_add_u32_e32 v5, 1, v0
	v_cmp_ge_u32_e32 vcc, v4, v3
	v_add_u32_e32 v4, 1, v6
	s_nop 0
	v_cndmask_b32_e32 v0, v0, v5, vcc
	v_mul_lo_u32 v5, v3, v0
	v_add_u32_e32 v3, v5, v3
	v_cmp_ne_u32_e32 vcc, v4, v3
	s_and_saveexec_b64 s[2:3], vcc
	s_xor_b64 s[2:3], exec, s[2:3]
	s_cbranch_execz .LBB0_420
	s_waitcnt lgkmcnt(0)
	v_add_u32_e32 v7, 1, v0
	v_mul_lo_u32 v7, v7, v2
	v_sub_u32_e32 v2, v6, v5
	v_sub_u32_e32 v4, v3, v5
	v_lshrrev_b32_e32 v4, 1, v4
	v_cmp_eq_u32_e32 vcc, v2, v4
	s_cbranch_vccz .Learlywb_skip0
	buffer_wbl2 sc1
.Learlywb_skip0:
	s_movk_i32 s86, 0xd00
	s_lshl_b64 s[4:5], s[86:87], 2
	v_readlane_b32 s6, v252, 44
	v_readlane_b32 s7, v252, 45
	s_add_u32 s6, s6, s4
	s_addc_u32 s7, s7, s5
	s_waitcnt lgkmcnt(0)
	s_nop 1
	buffer_inv sc1
	global_load_dword v2, v1, s[6:7] sc1
	s_waitcnt vmcnt(0)
	v_cmp_lt_u32_e32 vcc, v2, v7
	s_and_saveexec_b64 s[4:5], vcc
	s_cbranch_execz .LBB0_419
	s_mov_b32 s21, 1
	s_mov_b64 s[8:9], 0
	s_branch .LBB0_410

.LBB0_412:
	global_load_dword v2, v1, s[6:7] sc1
	s_add_i32 s21, s21, 1
	s_mov_b64 s[16:17], -1
	s_waitcnt vmcnt(0)
	v_cmp_ge_u32_e32 vcc, v2, v7
	s_orn2_b64 s[12:13], vcc, exec
	s_branch .LBB0_409

.LBB0_423:
	s_or_b64 exec, exec, s[4:5]
	s_waitcnt vmcnt(0)
	v_readfirstlane_b32 s2, v3
	v_sub_u32_e32 v4, 0, v2
	s_mov_b64 s[4:5], -1
	v_add_u32_e32 v3, s2, v0
	v_cvt_f32_u32_e32 v0, v2
	v_readlane_b32 s2, v253, 32
	v_readlane_b32 s3, v253, 33
	v_rcp_iflag_f32_e32 v0, v0
	s_nop 0
	v_mul_f32_e32 v0, 0x4f7ffffe, v0
	v_cvt_u32_f32_e32 v0, v0
	v_mul_lo_u32 v4, v4, v0
	v_mul_hi_u32 v4, v0, v4
	v_add_u32_e32 v0, v0, v4
	v_mul_hi_u32 v0, v3, v0
	v_mul_lo_u32 v4, v0, v2
	v_sub_u32_e32 v4, v3, v4
	v_cmp_ge_u32_e32 vcc, v4, v2
	v_add_u32_e32 v5, 1, v0
	v_add_u32_e32 v3, 1, v3
	v_cndmask_b32_e32 v0, v0, v5, vcc
	v_sub_u32_e32 v5, v4, v2
	v_cndmask_b32_e32 v4, v4, v5, vcc
	v_cmp_ge_u32_e32 vcc, v4, v2
	v_add_u32_e32 v4, 1, v0
	s_nop 0
	v_cndmask_b32_e32 v0, v0, v4, vcc
	v_mul_lo_u32 v4, v2, v0
	v_add_u32_e32 v2, v4, v2
	v_cmp_ne_u32_e32 vcc, v3, v2
	v_mov_b32_e32 v7, v2
	v_mov_b64_e32 v[2:3], s[2:3]
	s_and_saveexec_b64 s[2:3], vcc
	s_cbranch_execz .LBB0_435
	v_readlane_b32 s4, v253, 30
	v_readlane_b32 s5, v253, 31
	s_mov_b64 s[6:7], 0
	s_nop 3
	global_load_dword v2, v1, s[4:5] sc1
	s_waitcnt vmcnt(0)
	v_cmp_lt_u32_e32 vcc, v2, v7
	s_and_saveexec_b64 s[4:5], vcc
	s_cbranch_execz .LBB0_434
	s_mov_b32 s18, 1
	s_branch .LBB0_427

.LBB0_429:
	v_readlane_b32 s10, v253, 30
	v_readlane_b32 s11, v253, 31
	s_add_i32 s18, s18, 1
	s_mov_b64 s[12:13], -1
	s_nop 2
	global_load_dword v2, v1, s[10:11] sc1
	s_waitcnt vmcnt(0)
	v_cmp_ge_u32_e32 vcc, v2, v7
	s_orn2_b64 s[10:11], vcc, exec
	s_branch .LBB0_426

.LBB0_1067:
	global_load_dword v2, v1, s[6:7] sc1
	s_add_i32 s21, s21, 1
	s_mov_b64 s[64:65], -1
	s_waitcnt vmcnt(0)
	v_cmp_ge_u32_e32 vcc, v2, v7
	s_orn2_b64 s[34:35], vcc, exec
	s_branch .LBB0_1064

.LBB0_1078:
	s_or_b64 exec, exec, s[4:5]
	s_waitcnt vmcnt(0)
	v_readfirstlane_b32 s2, v3
	v_sub_u32_e32 v4, 0, v2
	s_mov_b64 s[4:5], -1
	v_add_u32_e32 v3, s2, v0
	v_cvt_f32_u32_e32 v0, v2
	v_readlane_b32 s2, v253, 32
	v_readlane_b32 s3, v253, 33
	v_rcp_iflag_f32_e32 v0, v0
	s_nop 0
	v_mul_f32_e32 v0, 0x4f7ffffe, v0
	v_cvt_u32_f32_e32 v0, v0
	v_mul_lo_u32 v4, v4, v0
	v_mul_hi_u32 v4, v0, v4
	v_add_u32_e32 v0, v0, v4
	v_mul_hi_u32 v0, v3, v0
	v_mul_lo_u32 v4, v0, v2
	v_sub_u32_e32 v4, v3, v4
	v_cmp_ge_u32_e32 vcc, v4, v2
	v_add_u32_e32 v5, 1, v0
	v_add_u32_e32 v3, 1, v3
	v_cndmask_b32_e32 v0, v0, v5, vcc
	v_sub_u32_e32 v5, v4, v2
	v_cndmask_b32_e32 v4, v4, v5, vcc
	v_cmp_ge_u32_e32 vcc, v4, v2
	v_add_u32_e32 v4, 1, v0
	s_nop 0
	v_cndmask_b32_e32 v0, v0, v4, vcc
	v_mul_lo_u32 v4, v2, v0
	v_add_u32_e32 v2, v4, v2
	v_cmp_ne_u32_e32 vcc, v3, v2
	v_mov_b32_e32 v7, v2
	v_mov_b64_e32 v[2:3], s[2:3]
	s_and_saveexec_b64 s[2:3], vcc
	s_cbranch_execz .LBB0_1090
	v_readlane_b32 s4, v253, 30
	v_readlane_b32 s5, v253, 31
	s_mov_b64 s[6:7], 0
	s_nop 3
	global_load_dword v2, v1, s[4:5] sc1
	s_waitcnt vmcnt(0)
	v_cmp_lt_u32_e32 vcc, v2, v7
	s_and_saveexec_b64 s[4:5], vcc
	s_cbranch_execz .LBB0_1089
	s_mov_b32 s21, 1
	s_branch .LBB0_1082

.LBB0_1084:
	v_readlane_b32 s18, v253, 30
	v_readlane_b32 s19, v253, 31
	s_add_i32 s21, s21, 1
	s_mov_b64 s[34:35], -1
	s_nop 2
	global_load_dword v2, v1, s[18:19] sc1
	s_waitcnt vmcnt(0)
	v_cmp_ge_u32_e32 vcc, v2, v7
	s_orn2_b64 s[18:19], vcc, exec
	s_branch .LBB0_1081

.LBB0_1268:
	s_or_b64 exec, exec, s[6:7]
	v_cvt_f32_u32_e32 v5, v3
	s_waitcnt vmcnt(0)
	v_readfirstlane_b32 s4, v4
	v_sub_u32_e32 v4, 0, v3
	v_rcp_iflag_f32_e32 v5, v5
	v_add_u32_e32 v6, s4, v0
	v_mul_f32_e32 v5, 0x4f7ffffe, v5
	v_cvt_u32_f32_e32 v5, v5
	v_mul_lo_u32 v0, v4, v5
	v_mul_hi_u32 v0, v5, v0
	v_add_u32_e32 v0, v5, v0
	v_mul_hi_u32 v0, v6, v0
	v_mul_lo_u32 v4, v0, v3
	v_sub_u32_e32 v4, v6, v4
	v_add_u32_e32 v5, 1, v0
	v_cmp_ge_u32_e32 vcc, v4, v3
	s_nop 1
	v_cndmask_b32_e32 v0, v0, v5, vcc
	v_sub_u32_e32 v5, v4, v3
	v_cndmask_b32_e32 v4, v4, v5, vcc
	v_add_u32_e32 v5, 1, v0
	v_cmp_ge_u32_e32 vcc, v4, v3
	v_add_u32_e32 v4, 1, v6
	s_nop 0
	v_cndmask_b32_e32 v0, v0, v5, vcc
	v_mul_lo_u32 v5, v3, v0
	v_add_u32_e32 v3, v5, v3
	v_cmp_ne_u32_e32 vcc, v4, v3
	s_and_saveexec_b64 s[4:5], vcc
	s_xor_b64 s[4:5], exec, s[4:5]
	s_cbranch_execz .LBB0_1282
	s_waitcnt lgkmcnt(0)
	v_add_u32_e32 v7, 1, v0
	v_mul_lo_u32 v7, v7, v2
	v_sub_u32_e32 v2, v6, v5
	v_sub_u32_e32 v4, v3, v5
	v_lshrrev_b32_e32 v4, 1, v4
	v_cmp_eq_u32_e32 vcc, v2, v4
	s_cbranch_vccz .Learlywb_skip7
	buffer_wbl2 sc1
.Learlywb_skip7:
	s_movk_i32 s86, 0xd00
	s_lshl_b64 s[6:7], s[86:87], 2
	v_readlane_b32 s8, v252, 44
	v_readlane_b32 s9, v252, 45
	s_add_u32 s8, s8, s6
	s_addc_u32 s9, s9, s7
	s_waitcnt lgkmcnt(0)
	s_nop 1
	buffer_inv sc1
	global_load_dword v2, v1, s[8:9] sc1
	s_waitcnt vmcnt(0)
	v_cmp_lt_u32_e32 vcc, v2, v7
	s_and_saveexec_b64 s[6:7], vcc
	s_cbranch_execz .LBB0_1281
	s_mov_b32 s21, 1
	s_mov_b64 s[10:11], 0
	s_branch .LBB0_1272

.LBB0_1274:
	global_load_dword v2, v1, s[8:9] sc1
	s_add_i32 s21, s21, 1
	s_mov_b64 s[18:19], -1
	s_waitcnt vmcnt(0)
	v_cmp_ge_u32_e32 vcc, v2, v7
	s_orn2_b64 s[16:17], vcc, exec
	s_branch .LBB0_1271

.LBB0_1285:
	s_or_b64 exec, exec, s[6:7]
	s_waitcnt vmcnt(0)
	v_readfirstlane_b32 s4, v3
	v_sub_u32_e32 v4, 0, v2
	s_mov_b64 s[6:7], -1
	v_add_u32_e32 v3, s4, v0
	v_cvt_f32_u32_e32 v0, v2
	v_readlane_b32 s4, v253, 32
	v_readlane_b32 s5, v253, 33
	v_rcp_iflag_f32_e32 v0, v0
	s_nop 0
	v_mul_f32_e32 v0, 0x4f7ffffe, v0
	v_cvt_u32_f32_e32 v0, v0
	v_mul_lo_u32 v4, v4, v0
	v_mul_hi_u32 v4, v0, v4
	v_add_u32_e32 v0, v0, v4
	v_mul_hi_u32 v0, v3, v0
	v_mul_lo_u32 v4, v0, v2
	v_sub_u32_e32 v4, v3, v4
	v_cmp_ge_u32_e32 vcc, v4, v2
	v_add_u32_e32 v5, 1, v0
	v_add_u32_e32 v3, 1, v3
	v_cndmask_b32_e32 v0, v0, v5, vcc
	v_sub_u32_e32 v5, v4, v2
	v_cndmask_b32_e32 v4, v4, v5, vcc
	v_cmp_ge_u32_e32 vcc, v4, v2
	v_add_u32_e32 v4, 1, v0
	s_nop 0
	v_cndmask_b32_e32 v0, v0, v4, vcc
	v_mul_lo_u32 v4, v2, v0
	v_add_u32_e32 v2, v4, v2
	v_cmp_ne_u32_e32 vcc, v3, v2
	v_mov_b32_e32 v7, v2
	v_mov_b64_e32 v[2:3], s[4:5]
	s_and_saveexec_b64 s[4:5], vcc
	s_cbranch_execz .LBB0_1297
	v_readlane_b32 s6, v253, 30
	v_readlane_b32 s7, v253, 31
	s_mov_b64 s[8:9], 0
	s_nop 3
	global_load_dword v2, v1, s[6:7] sc1
	s_waitcnt vmcnt(0)
	v_cmp_lt_u32_e32 vcc, v2, v7
	s_and_saveexec_b64 s[6:7], vcc
	s_cbranch_execz .LBB0_1296
	s_mov_b32 s21, 1
	s_branch .LBB0_1289

.LBB0_1291:
	v_readlane_b32 s12, v253, 30
	v_readlane_b32 s13, v253, 31
	s_add_i32 s21, s21, 1
	s_mov_b64 s[16:17], -1
	s_nop 2
	global_load_dword v2, v1, s[12:13] sc1
	s_waitcnt vmcnt(0)
	v_cmp_ge_u32_e32 vcc, v2, v7
	s_orn2_b64 s[12:13], vcc, exec
	s_branch .LBB0_1288
